# speedup vs baseline: 1.0037x; 1.0037x over previous
; #define WAIT_V(n) asm volatile("s_waitcnt vmcnt(" #n ")" ::: "memory")
; #define BAR __builtin_amdgcn_s_barrier()
; #define WAIT_V(n) asm volatile("s_waitcnt vmcnt(" #n ")" ::: "memory")
; #define BAR __builtin_amdgcn_s_barrier()
; __device__ __forceinline__ void gemm8_rt(const PRef& p, const bf16* __restrict__ A, const bf16* __restrict__ Bt, const int K, const int N, const int epi, const int splitS, float* __restrict__ outp, bf16* shm) {
;     ...
;   while (tile < nwg) {
;     const int brow = pm * BM, bcol = pn * BM;
;     f32x4 acc[2][2][4][2] = {};
;     bf16x8 At[4][2], B0[2][2], B1[2][2];
;     if (wr == 1) BAR;
;     WAIT_V(4); BAR;
;     STAGE(SB(1, 0), Bt, bcol, 1); STAGE(SA(1, 0), A, brow, 1); STAGE(SB(1, 1), Bt, bcol + HALF, 1);
;     WAIT_V(6); BAR;
.LBB0_346:
	s_or_b64 exec, exec, s[0:1]
	s_lshl_b32 s28, s24, 8
	s_mul_i32 s0, s28, s41
	s_add_i32 s1, s0, s46
	s_lshl_b32 s0, s1, 1
	s_mov_b32 m0, s48
	s_addk_i32 s0, 0x80
	s_mov_b32 s18, s78
	s_mov_b32 s19, s79
	s_lshl_b32 s82, s25, 8
	s_waitcnt vmcnt(4)
	s_barrier
	buffer_load_dwordx4 v172, s[16:19], s0 offen lds
	s_mov_b32 m0, s49
	s_add_i32 s1, s1, s66
	buffer_load_dwordx4 v173, s[16:19], s0 offen lds
	s_mul_i32 s0, s82, s41
	s_add_i32 s4, s46, s0
	s_lshl_b32 s4, s4, 1
	s_addk_i32 s4, 0x80
	s_mov_b32 m0, s51
	s_lshl_b32 s1, s1, 1
	buffer_load_dwordx4 v172, s[76:79], s4 offen lds
	s_mov_b32 m0, s52
	s_addk_i32 s1, 0x80
	buffer_load_dwordx4 v173, s[76:79], s4 offen lds
	s_mov_b32 m0, s53
	v_mov_b32_e32 v129, 0
	buffer_load_dwordx4 v172, s[16:19], s1 offen lds
	s_mov_b32 m0, s54
	s_cmp_lt_i32 s47, 3
	buffer_load_dwordx4 v173, s[16:19], s1 offen lds
	s_waitcnt vmcnt(6)
	v_mov_b32_e32 v128, v129
	v_mov_b32_e32 v127, v129
	v_mov_b32_e32 v126, v129
	v_mov_b32_e32 v125, v129
	v_mov_b32_e32 v124, v129
	v_mov_b32_e32 v123, v129
	v_mov_b32_e32 v122, v129
	v_mov_b32_e32 v121, v129
	v_mov_b32_e32 v120, v129
	v_mov_b32_e32 v119, v129
	v_mov_b32_e32 v118, v129
	v_mov_b32_e32 v117, v129
	v_mov_b32_e32 v116, v129
	v_mov_b32_e32 v115, v129
	v_mov_b32_e32 v114, v129
	v_mov_b32_e32 v113, v129
	v_mov_b32_e32 v112, v129
	v_mov_b32_e32 v111, v129
	v_mov_b32_e32 v110, v129
	v_mov_b32_e32 v109, v129
	v_mov_b32_e32 v108, v129
	v_mov_b32_e32 v107, v129
	v_mov_b32_e32 v106, v129
	v_mov_b32_e32 v105, v129
	v_mov_b32_e32 v104, v129
	v_mov_b32_e32 v103, v129
	v_mov_b32_e32 v102, v129
	v_mov_b32_e32 v101, v129
	v_mov_b32_e32 v100, v129
	v_mov_b32_e32 v99, v129
	v_mov_b32_e32 v98, v129
	v_mov_b32_e32 v97, v129
	v_mov_b32_e32 v96, v129
	v_mov_b32_e32 v95, v129
	v_mov_b32_e32 v94, v129
	v_mov_b32_e32 v93, v129
	v_mov_b32_e32 v92, v129
	v_mov_b32_e32 v91, v129
	v_mov_b32_e32 v90, v129
	v_mov_b32_e32 v89, v129
	v_mov_b32_e32 v88, v129
	v_mov_b32_e32 v87, v129
	v_mov_b32_e32 v86, v129
	v_mov_b32_e32 v85, v129
	v_mov_b32_e32 v84, v129
	v_mov_b32_e32 v83, v129
	v_mov_b32_e32 v82, v129
	v_mov_b32_e32 v81, v129
	v_mov_b32_e32 v80, v129
	v_mov_b32_e32 v79, v129
	v_mov_b32_e32 v78, v129
	v_mov_b32_e32 v77, v129
	v_mov_b32_e32 v76, v129
	v_mov_b32_e32 v75, v129
	v_mov_b32_e32 v74, v129
	v_mov_b32_e32 v73, v129
	v_mov_b32_e32 v72, v129
	v_mov_b32_e32 v71, v129
	v_mov_b32_e32 v70, v129
	v_mov_b32_e32 v69, v129
	v_mov_b32_e32 v68, v129
	v_mov_b32_e32 v67, v129
	v_mov_b32_e32 v66, v129
	v_mov_b32_e32 v65, v129
	v_mov_b32_e32 v64, v129
	v_mov_b32_e32 v63, v129
	v_mov_b32_e32 v62, v129
	v_mov_b32_e32 v61, v129
	v_mov_b32_e32 v60, v129
	v_mov_b32_e32 v59, v129
	v_mov_b32_e32 v58, v129
	v_mov_b32_e32 v57, v129
	v_mov_b32_e32 v56, v129
	v_mov_b32_e32 v55, v129
	v_mov_b32_e32 v54, v129
	v_mov_b32_e32 v53, v129
	v_mov_b32_e32 v52, v129
	v_mov_b32_e32 v51, v129
	v_mov_b32_e32 v50, v129
	v_mov_b32_e32 v49, v129
	v_mov_b32_e32 v48, v129
	v_mov_b32_e32 v47, v129
	v_mov_b32_e32 v46, v129
	v_mov_b32_e32 v45, v129
	v_mov_b32_e32 v44, v129
	v_mov_b32_e32 v43, v129
	v_mov_b32_e32 v42, v129
	v_mov_b32_e32 v41, v129
	v_mov_b32_e32 v40, v129
	v_mov_b32_e32 v39, v129
	v_mov_b32_e32 v38, v129
	v_mov_b32_e32 v37, v129
	v_mov_b32_e32 v36, v129
	v_mov_b32_e32 v35, v129
	v_mov_b32_e32 v34, v129
	v_mov_b32_e32 v33, v129
	v_mov_b32_e32 v32, v129
	v_mov_b32_e32 v31, v129
	v_mov_b32_e32 v30, v129
	v_mov_b32_e32 v29, v129
	v_mov_b32_e32 v28, v129
	v_mov_b32_e32 v27, v129
	v_mov_b32_e32 v26, v129
	v_mov_b32_e32 v25, v129
	v_mov_b32_e32 v24, v129
	v_mov_b32_e32 v23, v129
	v_mov_b32_e32 v22, v129
	v_mov_b32_e32 v21, v129
	v_mov_b32_e32 v20, v129
	v_mov_b32_e32 v19, v129
	v_mov_b32_e32 v18, v129
	v_mov_b32_e32 v17, v129
	v_mov_b32_e32 v16, v129
	v_mov_b32_e32 v15, v129
	v_mov_b32_e32 v14, v129
	v_mov_b32_e32 v13, v129
	v_mov_b32_e32 v12, v129
	v_mov_b32_e32 v11, v129
	v_mov_b32_e32 v10, v129
	v_mov_b32_e32 v9, v129
	v_mov_b32_e32 v8, v129
	v_mov_b32_e32 v7, v129
	v_mov_b32_e32 v6, v129
	v_mov_b32_e32 v5, v129
	v_mov_b32_e32 v4, v129
	v_mov_b32_e32 v3, v129
	v_mov_b32_e32 v2, v129
	s_barrier
	s_cbranch_scc1 .LBB0_349
	s_add_i32 s5, s82, 0x80
	s_mul_i32 s5, s70, s5
	s_add_i32 s10, s28, 0x80
	v_mov_b32_e32 v2, 0
	s_add_i32 s1, s47, -2
	s_lshl_b32 s4, s46, 1
	s_addk_i32 s5, 0x100
	s_mul_i32 s10, s70, s10
	s_mul_i32 s11, s71, s25
	s_mul_i32 s12, s71, s24
	s_mov_b32 s13, 0
	v_mov_b32_e32 v3, v2
	v_mov_b32_e32 v4, v2
	v_mov_b32_e32 v5, v2
	v_mov_b32_e32 v6, v2
	v_mov_b32_e32 v7, v2
	v_mov_b32_e32 v8, v2
	v_mov_b32_e32 v9, v2
	v_mov_b32_e32 v10, v2
	v_mov_b32_e32 v11, v2
	v_mov_b32_e32 v12, v2
	v_mov_b32_e32 v13, v2
	v_mov_b32_e32 v14, v2
	v_mov_b32_e32 v15, v2
	v_mov_b32_e32 v16, v2
	v_mov_b32_e32 v17, v2
	v_mov_b32_e32 v18, v2
	v_mov_b32_e32 v19, v2
	v_mov_b32_e32 v20, v2
	v_mov_b32_e32 v21, v2
	v_mov_b32_e32 v22, v2
	v_mov_b32_e32 v23, v2
	v_mov_b32_e32 v24, v2
	v_mov_b32_e32 v25, v2
	v_mov_b32_e32 v26, v2
	v_mov_b32_e32 v27, v2
	v_mov_b32_e32 v28, v2
	v_mov_b32_e32 v29, v2
	v_mov_b32_e32 v30, v2
	v_mov_b32_e32 v31, v2
	v_mov_b32_e32 v32, v2
	v_mov_b32_e32 v33, v2
	v_mov_b32_e32 v34, v2
	v_mov_b32_e32 v35, v2
	v_mov_b32_e32 v36, v2
	v_mov_b32_e32 v37, v2
	v_mov_b32_e32 v38, v2
	v_mov_b32_e32 v39, v2
	v_mov_b32_e32 v40, v2
	v_mov_b32_e32 v41, v2
	v_mov_b32_e32 v42, v2
	v_mov_b32_e32 v43, v2
	v_mov_b32_e32 v44, v2
	v_mov_b32_e32 v45, v2
	v_mov_b32_e32 v46, v2
	v_mov_b32_e32 v47, v2
	v_mov_b32_e32 v48, v2
	v_mov_b32_e32 v49, v2
	v_mov_b32_e32 v50, v2
	v_mov_b32_e32 v51, v2
	v_mov_b32_e32 v52, v2
	v_mov_b32_e32 v53, v2
	v_mov_b32_e32 v54, v2
	v_mov_b32_e32 v55, v2
	v_mov_b32_e32 v56, v2
	v_mov_b32_e32 v57, v2
; #define LDA(dst, b, h) for (int m = 0; m < 4; ++m) for (int k = 0; k < 2; ++k) \
;     dst[m][k] = *reinterpret_cast<const bf16x8*>((char*)SA(b, h) + lds_byte(wr * 64 + m * 16 + fr, k * 32 + fq * 8))
; #define LDB(dst, b, h) for (int n = 0; n < 2; ++n) for (int k = 0; k < 2; ++k) \
;     dst[n][k] = *reinterpret_cast<const bf16x8*>((char*)SB(b, h) + lds_byte(wc * 32 + n * 16 + fr, k * 32 + fq * 8))
; #define MMA(ai, bj, At, Bt_) do { __builtin_amdgcn_s_setprio(1); \
;     for (int m = 0; m < 4; ++m) for (int n = 0; n < 2; ++n) for (int k = 0; k < 2; ++k) \
;       acc[ai][bj][m][n] = __builtin_amdgcn_mfma_f32_16x16x32_bf16(At[m][k], Bt_[n][k], acc[ai][bj][m][n], 0, 0, 0); \
;     __builtin_amdgcn_s_setprio(0); } while (0)
; #define WAIT_V(n) asm volatile("s_waitcnt vmcnt(" #n ")" ::: "memory")
; #define WAIT_L(n) asm volatile("s_waitcnt lgkmcnt(" #n ")" ::: "memory")
; #define BAR __builtin_amdgcn_s_barrier()
; #define SCHED __builtin_amdgcn_sched_barrier(0)
; #define LDA(dst, b, h) for (int m = 0; m < 4; ++m) for (int k = 0; k < 2; ++k) \
;     dst[m][k] = *reinterpret_cast<const bf16x8*>((char*)SA(b, h) + lds_byte(wr * 64 + m * 16 + fr, k * 32 + fq * 8))
; #define LDB(dst, b, h) for (int n = 0; n < 2; ++n) for (int k = 0; k < 2; ++k) \
;     dst[n][k] = *reinterpret_cast<const bf16x8*>((char*)SB(b, h) + lds_byte(wc * 32 + n * 16 + fr, k * 32 + fq * 8))
; #define WAIT_V(n) asm volatile("s_waitcnt vmcnt(" #n ")" ::: "memory")
; #define WAIT_L(n) asm volatile("s_waitcnt lgkmcnt(" #n ")" ::: "memory")
; #define BAR __builtin_amdgcn_s_barrier()
; #define SCHED __builtin_amdgcn_sched_barrier(0)
; __device__ __forceinline__ void gemm8_rt(const PRef& p, const bf16* __restrict__ A, const bf16* __restrict__ Bt, const int K, const int N, const int epi, const int splitS, float* __restrict__ outp, bf16* shm) {
;     ...
;     f32x4 acc[2][2][4][2] = {};
;     bf16x8 At[4][2], B0[2][2], B1[2][2];
;     if (wr == 1) BAR;
;     WAIT_V(4); BAR;
;     STAGE(SB(1, 0), Bt, bcol, 1); STAGE(SA(1, 0), A, brow, 1); STAGE(SB(1, 1), Bt, bcol + HALF, 1);
;     WAIT_V(6); BAR;
;     for (int t = 0; t < nt - 2; t += 2) {
;       LDB(B0, 0, 0); SCHED; LDA(At, 0, 0); STAGE(SA(1, 1), A, brow + HALF, t + 1);
;       WAIT_L(8); BAR; WAIT_L(0); MMA(0, 0, At, B0); BAR; SCHED;
;       LDB(B1, 0, 1); STAGE(SB(0, 0), Bt, bcol, t + 2);
;       BAR; WAIT_L(0); MMA(0, 1, At, B1); BAR;
	v_mov_b32_e32 v58, v2
	v_mov_b32_e32 v59, v2
	v_mov_b32_e32 v60, v2
	v_mov_b32_e32 v61, v2
	v_mov_b32_e32 v62, v2
	v_mov_b32_e32 v63, v2
	v_mov_b32_e32 v64, v2
	v_mov_b32_e32 v65, v2
	v_mov_b32_e32 v66, v2
	v_mov_b32_e32 v67, v2
	v_mov_b32_e32 v68, v2
	v_mov_b32_e32 v69, v2
	v_mov_b32_e32 v70, v2
	v_mov_b32_e32 v71, v2
	v_mov_b32_e32 v72, v2
	v_mov_b32_e32 v73, v2
	v_mov_b32_e32 v74, v2
	v_mov_b32_e32 v75, v2
	v_mov_b32_e32 v76, v2
	v_mov_b32_e32 v77, v2
	v_mov_b32_e32 v78, v2
	v_mov_b32_e32 v79, v2
	v_mov_b32_e32 v80, v2
	v_mov_b32_e32 v81, v2
	v_mov_b32_e32 v82, v2
	v_mov_b32_e32 v83, v2
	v_mov_b32_e32 v84, v2
	v_mov_b32_e32 v85, v2
	v_mov_b32_e32 v86, v2
	v_mov_b32_e32 v87, v2
	v_mov_b32_e32 v88, v2
	v_mov_b32_e32 v89, v2
	v_mov_b32_e32 v90, v2
	v_mov_b32_e32 v91, v2
	v_mov_b32_e32 v92, v2
	v_mov_b32_e32 v93, v2
	v_mov_b32_e32 v94, v2
	v_mov_b32_e32 v95, v2
	v_mov_b32_e32 v96, v2
	v_mov_b32_e32 v97, v2
	v_mov_b32_e32 v98, v2
	v_mov_b32_e32 v99, v2
	v_mov_b32_e32 v100, v2
	v_mov_b32_e32 v101, v2
	v_mov_b32_e32 v102, v2
	v_mov_b32_e32 v103, v2
	v_mov_b32_e32 v104, v2
	v_mov_b32_e32 v105, v2
	v_mov_b32_e32 v106, v2
	v_mov_b32_e32 v107, v2
	v_mov_b32_e32 v108, v2
	v_mov_b32_e32 v109, v2
	v_mov_b32_e32 v110, v2
	v_mov_b32_e32 v111, v2
	v_mov_b32_e32 v112, v2
	v_mov_b32_e32 v113, v2
	v_mov_b32_e32 v114, v2
	v_mov_b32_e32 v115, v2
	v_mov_b32_e32 v116, v2
	v_mov_b32_e32 v117, v2
	v_mov_b32_e32 v118, v2
	v_mov_b32_e32 v119, v2
	v_mov_b32_e32 v120, v2
	v_mov_b32_e32 v121, v2
	v_mov_b32_e32 v122, v2
	v_mov_b32_e32 v123, v2
	v_mov_b32_e32 v124, v2
	v_mov_b32_e32 v125, v2
	v_mov_b32_e32 v126, v2
	v_mov_b32_e32 v127, v2
	v_mov_b32_e32 v128, v2
	v_mov_b32_e32 v129, v2
	v_readfirstlane_b32 s101, v171
	s_bitcmp1_b32 s101, 8
	s_cbranch_scc0 .Lmy_prio_skip
	s_setprio 1
.Lmy_prio_skip:
.LBB0_348:
	v_add_u32_e32 v0, v175, v174
	ds_read_b128 v[130:133], v0
	ds_read_b128 v[134:137], v0 offset:1024
	ds_read_b128 v[138:141], v0 offset:2048
	ds_read_b128 v[146:149], v0 offset:3072
	s_add_i32 s22, s4, s5
	v_add_u32_e32 v0, v183, v179
	v_add_u32_e32 v142, v184, v180
	v_add_u32_e32 v143, v184, v181
	v_add_u32_e32 v144, v184, v182
	s_add_i32 s18, s22, 0xffffff80
	s_mov_b32 m0, s55
	ds_read_b128 v[150:153], v0
	ds_read_b128 v[154:157], v0 offset:1024
	ds_read_b128 v[158:161], v142
	ds_read_b128 v[162:165], v142 offset:1024
	ds_read_b128 v[166:169], v143
	ds_read_b128 v[186:189], v143 offset:1024
	ds_read_b128 v[196:199], v144
	ds_read_b128 v[200:203], v144 offset:1024
	buffer_load_dwordx4 v172, s[76:79], s18 offen lds
	s_mov_b32 m0, s56
	s_nop 0
	buffer_load_dwordx4 v173, s[76:79], s18 offen lds
	s_waitcnt lgkmcnt(8)
	s_barrier
	s_waitcnt lgkmcnt(0)
	s_waitcnt lgkmcnt(7)
	v_mfma_f32_16x16x32_bf16 v[126:129], v[150:153], v[130:133], v[126:129]
	v_mfma_f32_16x16x32_bf16 v[122:125], v[150:153], v[138:141], v[122:125]
	s_waitcnt lgkmcnt(5)
	v_mfma_f32_16x16x32_bf16 v[118:121], v[158:161], v[130:133], v[118:121]
	v_mfma_f32_16x16x32_bf16 v[114:117], v[158:161], v[138:141], v[114:117]
	s_waitcnt lgkmcnt(3)
	v_mfma_f32_16x16x32_bf16 v[110:113], v[166:169], v[130:133], v[110:113]
	v_mfma_f32_16x16x32_bf16 v[106:109], v[166:169], v[138:141], v[106:109]
	s_waitcnt lgkmcnt(1)
	v_mfma_f32_16x16x32_bf16 v[102:105], v[196:199], v[130:133], v[102:105]
	v_mfma_f32_16x16x32_bf16 v[98:101], v[196:199], v[138:141], v[98:101]
	v_mfma_f32_16x16x32_bf16 v[126:129], v[154:157], v[134:137], v[126:129]
	v_mfma_f32_16x16x32_bf16 v[122:125], v[154:157], v[146:149], v[122:125]
	v_mfma_f32_16x16x32_bf16 v[118:121], v[162:165], v[134:137], v[118:121]
	v_mfma_f32_16x16x32_bf16 v[114:117], v[162:165], v[146:149], v[114:117]
	v_mfma_f32_16x16x32_bf16 v[110:113], v[186:189], v[134:137], v[110:113]
	v_mfma_f32_16x16x32_bf16 v[106:109], v[186:189], v[146:149], v[106:109]
	s_waitcnt lgkmcnt(0)
	v_mfma_f32_16x16x32_bf16 v[102:105], v[200:203], v[134:137], v[102:105]
	v_mfma_f32_16x16x32_bf16 v[98:101], v[200:203], v[146:149], v[98:101]
	s_barrier
	s_add_i32 s23, s4, s12
	s_mov_b32 m0, s57
	v_add_u32_e32 v185, v176, v174
	s_add_i32 s27, s23, 0x100
	s_mov_b32 s18, s78
	s_mov_b32 s19, s79
	ds_read_b128 v[204:207], v185
	ds_read_b128 v[212:215], v185 offset:1024
	ds_read_b128 v[216:219], v185 offset:2048
	ds_read_b128 v[220:223], v185 offset:3072
	buffer_load_dwordx4 v172, s[16:19], s27 offen lds
	s_mov_b32 m0, s58
	s_add_i32 s13, s13, 2
	buffer_load_dwordx4 v173, s[16:19], s27 offen lds
	s_barrier
	s_waitcnt lgkmcnt(0)
	s_waitcnt lgkmcnt(3)
	v_mfma_f32_16x16x32_bf16 v[94:97], v[150:153], v[204:207], v[94:97]
	s_waitcnt lgkmcnt(1)
	v_mfma_f32_16x16x32_bf16 v[90:93], v[150:153], v[216:219], v[90:93]
	v_mfma_f32_16x16x32_bf16 v[86:89], v[158:161], v[204:207], v[86:89]
	v_mfma_f32_16x16x32_bf16 v[82:85], v[158:161], v[216:219], v[82:85]
	v_mfma_f32_16x16x32_bf16 v[78:81], v[166:169], v[204:207], v[78:81]
	v_mfma_f32_16x16x32_bf16 v[74:77], v[166:169], v[216:219], v[74:77]
	v_mfma_f32_16x16x32_bf16 v[70:73], v[196:199], v[204:207], v[70:73]
	v_mfma_f32_16x16x32_bf16 v[66:69], v[196:199], v[216:219], v[66:69]
	v_mfma_f32_16x16x32_bf16 v[94:97], v[154:157], v[212:215], v[94:97]
	s_waitcnt lgkmcnt(0)
	v_mfma_f32_16x16x32_bf16 v[90:93], v[154:157], v[220:223], v[90:93]
	v_mfma_f32_16x16x32_bf16 v[86:89], v[162:165], v[212:215], v[86:89]
	v_mfma_f32_16x16x32_bf16 v[82:85], v[162:165], v[220:223], v[82:85]
	v_mfma_f32_16x16x32_bf16 v[78:81], v[186:189], v[212:215], v[78:81]
	v_mfma_f32_16x16x32_bf16 v[74:77], v[186:189], v[220:223], v[74:77]
	v_mfma_f32_16x16x32_bf16 v[70:73], v[200:203], v[212:215], v[70:73]
	v_mfma_f32_16x16x32_bf16 v[66:69], v[200:203], v[220:223], v[66:69]
	s_add_i32 s27, s4, s11
	s_add_i32 s29, s27, 0x100
	s_mov_b32 m0, s50
	s_barrier
; #define LDA(dst, b, h) for (int m = 0; m < 4; ++m) for (int k = 0; k < 2; ++k) \
;     dst[m][k] = *reinterpret_cast<const bf16x8*>((char*)SA(b, h) + lds_byte(wr * 64 + m * 16 + fr, k * 32 + fq * 8))
; #define LDB(dst, b, h) for (int n = 0; n < 2; ++n) for (int k = 0; k < 2; ++k) \
;     dst[n][k] = *reinterpret_cast<const bf16x8*>((char*)SB(b, h) + lds_byte(wc * 32 + n * 16 + fr, k * 32 + fq * 8))
; #define MMA(ai, bj, At, Bt_) do { __builtin_amdgcn_s_setprio(1); \
;     for (int m = 0; m < 4; ++m) for (int n = 0; n < 2; ++n) for (int k = 0; k < 2; ++k) \
;       acc[ai][bj][m][n] = __builtin_amdgcn_mfma_f32_16x16x32_bf16(At[m][k], Bt_[n][k], acc[ai][bj][m][n], 0, 0, 0); \
;     __builtin_amdgcn_s_setprio(0); } while (0)
; #define WAIT_V(n) asm volatile("s_waitcnt vmcnt(" #n ")" ::: "memory")
; #define WAIT_L(n) asm volatile("s_waitcnt lgkmcnt(" #n ")" ::: "memory")
; #define BAR __builtin_amdgcn_s_barrier()
; #define SCHED __builtin_amdgcn_sched_barrier(0)
; #define LDA(dst, b, h) for (int m = 0; m < 4; ++m) for (int k = 0; k < 2; ++k) \
;     dst[m][k] = *reinterpret_cast<const bf16x8*>((char*)SA(b, h) + lds_byte(wr * 64 + m * 16 + fr, k * 32 + fq * 8))
; #define LDB(dst, b, h) for (int n = 0; n < 2; ++n) for (int k = 0; k < 2; ++k) \
;     dst[n][k] = *reinterpret_cast<const bf16x8*>((char*)SB(b, h) + lds_byte(wc * 32 + n * 16 + fr, k * 32 + fq * 8))
; #define MMA(ai, bj, At, Bt_) do { __builtin_amdgcn_s_setprio(1); \
;     for (int m = 0; m < 4; ++m) for (int n = 0; n < 2; ++n) for (int k = 0; k < 2; ++k) \
;       acc[ai][bj][m][n] = __builtin_amdgcn_mfma_f32_16x16x32_bf16(At[m][k], Bt_[n][k], acc[ai][bj][m][n], 0, 0, 0); \
;     __builtin_amdgcn_s_setprio(0); } while (0)
; #define WAIT_V(n) asm volatile("s_waitcnt vmcnt(" #n ")" ::: "memory")
; #define BAR __builtin_amdgcn_s_barrier()
; __device__ __forceinline__ void gemm8_rt(const PRef& p, const bf16* __restrict__ A, const bf16* __restrict__ Bt, const int K, const int N, const int epi, const int splitS, float* __restrict__ outp, bf16* shm) {
;     ...
;       LDA(At, 0, 1); STAGE(SA(0, 0), A, brow, t + 2);
;       BAR; WAIT_L(0); MMA(1, 0, At, B0); BAR; SCHED;
;       STAGE(SB(0, 1), Bt, bcol + HALF, t + 2);
;       WAIT_V(6); BAR; MMA(1, 1, At, B1); BAR;
;       LDB(B0, 1, 0); SCHED; LDA(At, 1, 0); STAGE(SA(0, 1), A, brow + HALF, t + 2);
;       WAIT_L(8); BAR; WAIT_L(0); MMA(0, 0, At, B0); BAR; SCHED;
	ds_read_b128 v[150:153], v0 offset:16384
	ds_read_b128 v[154:157], v0 offset:17408
	ds_read_b128 v[158:161], v142 offset:16384
	ds_read_b128 v[162:165], v142 offset:17408
	ds_read_b128 v[166:169], v143 offset:16384
	ds_read_b128 v[186:189], v143 offset:17408
	ds_read_b128 v[196:199], v144 offset:16384
	ds_read_b128 v[200:203], v144 offset:17408
	buffer_load_dwordx4 v172, s[76:79], s29 offen lds
	s_mov_b32 m0, s59
	s_nop 0
	buffer_load_dwordx4 v173, s[76:79], s29 offen lds
	s_barrier
	s_waitcnt lgkmcnt(0)
	s_waitcnt lgkmcnt(7)
	v_mfma_f32_16x16x32_bf16 v[62:65], v[150:153], v[130:133], v[62:65]
	v_mfma_f32_16x16x32_bf16 v[58:61], v[150:153], v[138:141], v[58:61]
	s_waitcnt lgkmcnt(5)
	v_mfma_f32_16x16x32_bf16 v[54:57], v[158:161], v[130:133], v[54:57]
	v_mfma_f32_16x16x32_bf16 v[50:53], v[158:161], v[138:141], v[50:53]
	s_waitcnt lgkmcnt(3)
	v_mfma_f32_16x16x32_bf16 v[46:49], v[166:169], v[130:133], v[46:49]
	v_mfma_f32_16x16x32_bf16 v[42:45], v[166:169], v[138:141], v[42:45]
	s_waitcnt lgkmcnt(1)
	v_mfma_f32_16x16x32_bf16 v[38:41], v[196:199], v[130:133], v[38:41]
	v_mfma_f32_16x16x32_bf16 v[34:37], v[196:199], v[138:141], v[34:37]
	v_mfma_f32_16x16x32_bf16 v[62:65], v[154:157], v[134:137], v[62:65]
	v_mfma_f32_16x16x32_bf16 v[58:61], v[154:157], v[146:149], v[58:61]
	v_mfma_f32_16x16x32_bf16 v[54:57], v[162:165], v[134:137], v[54:57]
	v_mfma_f32_16x16x32_bf16 v[50:53], v[162:165], v[146:149], v[50:53]
	v_mfma_f32_16x16x32_bf16 v[46:49], v[186:189], v[134:137], v[46:49]
	v_mfma_f32_16x16x32_bf16 v[42:45], v[186:189], v[146:149], v[42:45]
	s_waitcnt lgkmcnt(0)
	v_mfma_f32_16x16x32_bf16 v[38:41], v[200:203], v[134:137], v[38:41]
	v_mfma_f32_16x16x32_bf16 v[34:37], v[200:203], v[146:149], v[34:37]
	s_barrier
	s_add_i32 s29, s4, s10
	s_add_i32 s30, s29, 0x100
	s_mov_b32 m0, s60
	s_nop 0
	buffer_load_dwordx4 v172, s[16:19], s30 offen lds
	s_mov_b32 m0, s61
	s_nop 0
	buffer_load_dwordx4 v173, s[16:19], s30 offen lds
	s_waitcnt vmcnt(6)
	s_barrier
	v_mfma_f32_16x16x32_bf16 v[30:33], v[150:153], v[204:207], v[30:33]
	v_mfma_f32_16x16x32_bf16 v[26:29], v[150:153], v[216:219], v[26:29]
	v_mfma_f32_16x16x32_bf16 v[22:25], v[158:161], v[204:207], v[22:25]
	v_mfma_f32_16x16x32_bf16 v[18:21], v[158:161], v[216:219], v[18:21]
	v_mfma_f32_16x16x32_bf16 v[14:17], v[166:169], v[204:207], v[14:17]
	v_mfma_f32_16x16x32_bf16 v[10:13], v[166:169], v[216:219], v[10:13]
	v_mfma_f32_16x16x32_bf16 v[6:9], v[196:199], v[204:207], v[6:9]
	v_mfma_f32_16x16x32_bf16 v[2:5], v[196:199], v[216:219], v[2:5]
	v_mfma_f32_16x16x32_bf16 v[30:33], v[154:157], v[212:215], v[30:33]
	v_mfma_f32_16x16x32_bf16 v[26:29], v[154:157], v[220:223], v[26:29]
	v_mfma_f32_16x16x32_bf16 v[22:25], v[162:165], v[212:215], v[22:25]
	v_mfma_f32_16x16x32_bf16 v[18:21], v[162:165], v[220:223], v[18:21]
	v_mfma_f32_16x16x32_bf16 v[14:17], v[186:189], v[212:215], v[14:17]
	v_mfma_f32_16x16x32_bf16 v[10:13], v[186:189], v[220:223], v[10:13]
	v_mfma_f32_16x16x32_bf16 v[6:9], v[200:203], v[212:215], v[6:9]
	v_mfma_f32_16x16x32_bf16 v[2:5], v[200:203], v[220:223], v[2:5]
	v_add_u32_e32 v146, v177, v174
	s_barrier
	ds_read_b128 v[130:133], v146
	ds_read_b128 v[134:137], v146 offset:1024
	ds_read_b128 v[138:141], v146 offset:2048
	ds_read_b128 v[146:149], v146 offset:3072
	s_mov_b32 m0, s62
	ds_read_b128 v[150:153], v0 offset:32768
	ds_read_b128 v[154:157], v0 offset:33792
	ds_read_b128 v[158:161], v142 offset:32768
	ds_read_b128 v[162:165], v142 offset:33792
	ds_read_b128 v[166:169], v143 offset:32768
	ds_read_b128 v[186:189], v143 offset:33792
	ds_read_b128 v[196:199], v144 offset:32768
	ds_read_b128 v[200:203], v144 offset:33792
	buffer_load_dwordx4 v172, s[76:79], s22 offen lds
	s_mov_b32 m0, s63
	s_nop 0
	buffer_load_dwordx4 v173, s[76:79], s22 offen lds
	s_waitcnt lgkmcnt(8)
	s_barrier
	s_waitcnt lgkmcnt(0)
	s_waitcnt lgkmcnt(7)
	v_mfma_f32_16x16x32_bf16 v[126:129], v[150:153], v[130:133], v[126:129]
	v_mfma_f32_16x16x32_bf16 v[122:125], v[150:153], v[138:141], v[122:125]
	s_waitcnt lgkmcnt(5)
	v_mfma_f32_16x16x32_bf16 v[118:121], v[158:161], v[130:133], v[118:121]
	v_mfma_f32_16x16x32_bf16 v[114:117], v[158:161], v[138:141], v[114:117]
	s_waitcnt lgkmcnt(3)
	v_mfma_f32_16x16x32_bf16 v[110:113], v[166:169], v[130:133], v[110:113]
	v_mfma_f32_16x16x32_bf16 v[106:109], v[166:169], v[138:141], v[106:109]
	s_waitcnt lgkmcnt(1)
	v_mfma_f32_16x16x32_bf16 v[102:105], v[196:199], v[130:133], v[102:105]
	v_mfma_f32_16x16x32_bf16 v[98:101], v[196:199], v[138:141], v[98:101]
	v_mfma_f32_16x16x32_bf16 v[126:129], v[154:157], v[134:137], v[126:129]
	v_mfma_f32_16x16x32_bf16 v[122:125], v[154:157], v[146:149], v[122:125]
	v_mfma_f32_16x16x32_bf16 v[118:121], v[162:165], v[134:137], v[118:121]
	v_mfma_f32_16x16x32_bf16 v[114:117], v[162:165], v[146:149], v[114:117]
	v_mfma_f32_16x16x32_bf16 v[110:113], v[186:189], v[134:137], v[110:113]
	v_mfma_f32_16x16x32_bf16 v[106:109], v[186:189], v[146:149], v[106:109]
	s_waitcnt lgkmcnt(0)
	v_mfma_f32_16x16x32_bf16 v[102:105], v[200:203], v[134:137], v[102:105]
	v_mfma_f32_16x16x32_bf16 v[98:101], v[200:203], v[146:149], v[98:101]
	s_barrier
; #define LDA(dst, b, h) for (int m = 0; m < 4; ++m) for (int k = 0; k < 2; ++k) \
;     dst[m][k] = *reinterpret_cast<const bf16x8*>((char*)SA(b, h) + lds_byte(wr * 64 + m * 16 + fr, k * 32 + fq * 8))
; #define LDB(dst, b, h) for (int n = 0; n < 2; ++n) for (int k = 0; k < 2; ++k) \
;     dst[n][k] = *reinterpret_cast<const bf16x8*>((char*)SB(b, h) + lds_byte(wc * 32 + n * 16 + fr, k * 32 + fq * 8))
; #define MMA(ai, bj, At, Bt_) do { __builtin_amdgcn_s_setprio(1); \
;     for (int m = 0; m < 4; ++m) for (int n = 0; n < 2; ++n) for (int k = 0; k < 2; ++k) \
;       acc[ai][bj][m][n] = __builtin_amdgcn_mfma_f32_16x16x32_bf16(At[m][k], Bt_[n][k], acc[ai][bj][m][n], 0, 0, 0); \
;     __builtin_amdgcn_s_setprio(0); } while (0)
; #define WAIT_V(n) asm volatile("s_waitcnt vmcnt(" #n ")" ::: "memory")
; #define WAIT_L(n) asm volatile("s_waitcnt lgkmcnt(" #n ")" ::: "memory")
; #define BAR __builtin_amdgcn_s_barrier()
; #define SCHED __builtin_amdgcn_sched_barrier(0)
; #define LDA(dst, b, h) for (int m = 0; m < 4; ++m) for (int k = 0; k < 2; ++k) \
;     dst[m][k] = *reinterpret_cast<const bf16x8*>((char*)SA(b, h) + lds_byte(wr * 64 + m * 16 + fr, k * 32 + fq * 8))
; #define LDB(dst, b, h) for (int n = 0; n < 2; ++n) for (int k = 0; k < 2; ++k) \
;     dst[n][k] = *reinterpret_cast<const bf16x8*>((char*)SB(b, h) + lds_byte(wc * 32 + n * 16 + fr, k * 32 + fq * 8))
; #define MMA(ai, bj, At, Bt_) do { __builtin_amdgcn_s_setprio(1); \
;     for (int m = 0; m < 4; ++m) for (int n = 0; n < 2; ++n) for (int k = 0; k < 2; ++k) \
;       acc[ai][bj][m][n] = __builtin_amdgcn_mfma_f32_16x16x32_bf16(At[m][k], Bt_[n][k], acc[ai][bj][m][n], 0, 0, 0); \
;     __builtin_amdgcn_s_setprio(0); } while (0)
; #define WAIT_V(n) asm volatile("s_waitcnt vmcnt(" #n ")" ::: "memory")
; #define WAIT_L(n) asm volatile("s_waitcnt lgkmcnt(" #n ")" ::: "memory")
; __device__ __forceinline__ void gemm8_rt(const PRef& p, const bf16* __restrict__ A, const bf16* __restrict__ Bt, const int K, const int N, const int epi, const int splitS, float* __restrict__ outp, bf16* shm) {
;     ...
;       LDB(B1, 1, 1); STAGE(SB(1, 0), Bt, bcol, t + 3);
;       BAR; WAIT_L(0); MMA(0, 1, At, B1); BAR;
;       LDA(At, 1, 1); STAGE(SA(1, 0), A, brow, t + 3);
;       BAR; WAIT_L(0); MMA(1, 0, At, B0); BAR; SCHED;
;       STAGE(SB(1, 1), Bt, bcol + HALF, t + 3);
;       WAIT_V(6); BAR; MMA(1, 1, At, B1); BAR;
;     }
	v_add_u32_e32 v185, v178, v174
	s_addk_i32 s23, 0x180
	s_mov_b32 m0, s48
	ds_read_b128 v[204:207], v185
	ds_read_b128 v[212:215], v185 offset:1024
	ds_read_b128 v[216:219], v185 offset:2048
	ds_read_b128 v[220:223], v185 offset:3072
	buffer_load_dwordx4 v172, s[16:19], s23 offen lds
	s_mov_b32 m0, s49
	s_nop 0
	buffer_load_dwordx4 v173, s[16:19], s23 offen lds
	s_barrier
	s_waitcnt lgkmcnt(0)
	s_waitcnt lgkmcnt(3)
	v_mfma_f32_16x16x32_bf16 v[94:97], v[150:153], v[204:207], v[94:97]
	s_waitcnt lgkmcnt(1)
	v_mfma_f32_16x16x32_bf16 v[90:93], v[150:153], v[216:219], v[90:93]
	v_mfma_f32_16x16x32_bf16 v[86:89], v[158:161], v[204:207], v[86:89]
	v_mfma_f32_16x16x32_bf16 v[82:85], v[158:161], v[216:219], v[82:85]
	v_mfma_f32_16x16x32_bf16 v[78:81], v[166:169], v[204:207], v[78:81]
	v_mfma_f32_16x16x32_bf16 v[74:77], v[166:169], v[216:219], v[74:77]
	v_mfma_f32_16x16x32_bf16 v[70:73], v[196:199], v[204:207], v[70:73]
	v_mfma_f32_16x16x32_bf16 v[66:69], v[196:199], v[216:219], v[66:69]
	v_mfma_f32_16x16x32_bf16 v[94:97], v[154:157], v[212:215], v[94:97]
	s_waitcnt lgkmcnt(0)
	v_mfma_f32_16x16x32_bf16 v[90:93], v[154:157], v[220:223], v[90:93]
	v_mfma_f32_16x16x32_bf16 v[86:89], v[162:165], v[212:215], v[86:89]
	v_mfma_f32_16x16x32_bf16 v[82:85], v[162:165], v[220:223], v[82:85]
	v_mfma_f32_16x16x32_bf16 v[78:81], v[186:189], v[212:215], v[78:81]
	v_mfma_f32_16x16x32_bf16 v[74:77], v[186:189], v[220:223], v[74:77]
	v_mfma_f32_16x16x32_bf16 v[70:73], v[200:203], v[212:215], v[70:73]
	v_mfma_f32_16x16x32_bf16 v[66:69], v[200:203], v[220:223], v[66:69]
	s_addk_i32 s27, 0x180
	s_mov_b32 m0, s51
	s_barrier
	ds_read_b128 v[150:153], v0 offset:49152
	ds_read_b128 v[154:157], v0 offset:50176
	ds_read_b128 v[158:161], v142 offset:49152
	ds_read_b128 v[162:165], v142 offset:50176
	ds_read_b128 v[166:169], v143 offset:49152
	ds_read_b128 v[186:189], v143 offset:50176
	ds_read_b128 v[196:199], v144 offset:49152
	ds_read_b128 v[200:203], v144 offset:50176
	buffer_load_dwordx4 v172, s[76:79], s27 offen lds
	s_mov_b32 m0, s52
	s_nop 0
	buffer_load_dwordx4 v173, s[76:79], s27 offen lds
	s_barrier
	s_waitcnt lgkmcnt(0)
	s_waitcnt lgkmcnt(7)
	v_mfma_f32_16x16x32_bf16 v[62:65], v[150:153], v[130:133], v[62:65]
	v_mfma_f32_16x16x32_bf16 v[58:61], v[150:153], v[138:141], v[58:61]
	s_waitcnt lgkmcnt(5)
	v_mfma_f32_16x16x32_bf16 v[54:57], v[158:161], v[130:133], v[54:57]
	v_mfma_f32_16x16x32_bf16 v[50:53], v[158:161], v[138:141], v[50:53]
	s_waitcnt lgkmcnt(3)
	v_mfma_f32_16x16x32_bf16 v[46:49], v[166:169], v[130:133], v[46:49]
	v_mfma_f32_16x16x32_bf16 v[42:45], v[166:169], v[138:141], v[42:45]
	s_waitcnt lgkmcnt(1)
	v_mfma_f32_16x16x32_bf16 v[38:41], v[196:199], v[130:133], v[38:41]
	v_mfma_f32_16x16x32_bf16 v[34:37], v[196:199], v[138:141], v[34:37]
	v_mfma_f32_16x16x32_bf16 v[62:65], v[154:157], v[134:137], v[62:65]
	v_mfma_f32_16x16x32_bf16 v[58:61], v[154:157], v[146:149], v[58:61]
	v_mfma_f32_16x16x32_bf16 v[54:57], v[162:165], v[134:137], v[54:57]
	v_mfma_f32_16x16x32_bf16 v[50:53], v[162:165], v[146:149], v[50:53]
	v_mfma_f32_16x16x32_bf16 v[46:49], v[186:189], v[134:137], v[46:49]
	v_mfma_f32_16x16x32_bf16 v[42:45], v[186:189], v[146:149], v[42:45]
	s_waitcnt lgkmcnt(0)
	v_mfma_f32_16x16x32_bf16 v[38:41], v[200:203], v[134:137], v[38:41]
	v_mfma_f32_16x16x32_bf16 v[34:37], v[200:203], v[146:149], v[34:37]
	s_barrier
	s_addk_i32 s29, 0x180
	s_mov_b32 m0, s53
	s_nop 0
	buffer_load_dwordx4 v172, s[16:19], s29 offen lds
	s_mov_b32 m0, s54
	s_nop 0
	buffer_load_dwordx4 v173, s[16:19], s29 offen lds
	s_waitcnt vmcnt(6)
	s_barrier
	v_mfma_f32_16x16x32_bf16 v[30:33], v[150:153], v[204:207], v[30:33]
	v_mfma_f32_16x16x32_bf16 v[26:29], v[150:153], v[216:219], v[26:29]
	v_mfma_f32_16x16x32_bf16 v[22:25], v[158:161], v[204:207], v[22:25]
	v_mfma_f32_16x16x32_bf16 v[18:21], v[158:161], v[216:219], v[18:21]
	v_mfma_f32_16x16x32_bf16 v[14:17], v[166:169], v[204:207], v[14:17]
	v_mfma_f32_16x16x32_bf16 v[10:13], v[166:169], v[216:219], v[10:13]
	v_mfma_f32_16x16x32_bf16 v[6:9], v[196:199], v[204:207], v[6:9]
	v_mfma_f32_16x16x32_bf16 v[2:5], v[196:199], v[216:219], v[2:5]
	v_mfma_f32_16x16x32_bf16 v[30:33], v[154:157], v[212:215], v[30:33]
	v_mfma_f32_16x16x32_bf16 v[26:29], v[154:157], v[220:223], v[26:29]
	v_mfma_f32_16x16x32_bf16 v[22:25], v[162:165], v[212:215], v[22:25]
	v_mfma_f32_16x16x32_bf16 v[18:21], v[162:165], v[220:223], v[18:21]
	v_mfma_f32_16x16x32_bf16 v[14:17], v[186:189], v[212:215], v[14:17]
	v_mfma_f32_16x16x32_bf16 v[10:13], v[186:189], v[220:223], v[10:13]
	v_mfma_f32_16x16x32_bf16 v[6:9], v[200:203], v[212:215], v[6:9]
	v_mfma_f32_16x16x32_bf16 v[2:5], v[200:203], v[220:223], v[2:5]
	s_addk_i32 s5, 0x100
	s_addk_i32 s10, 0x100
	s_addk_i32 s11, 0x100
	s_addk_i32 s12, 0x100
	s_cmp_ge_i32 s13, s1
	s_barrier
	s_cbranch_scc0 .LBB0_348

; #define BAR __builtin_amdgcn_s_barrier()
; #define BAR __builtin_amdgcn_s_barrier()
; #define PRO_STAGE(BR, BC) do { STAGE(SB(0, 0), Bt, (BC), 0); STAGE(SA(0, 0), A, (BR), 0); STAGE(SB(0, 1), Bt, (BC) + HALF, 0); STAGE(SA(0, 1), A, (BR) + HALF, 0); } while (0)
; __device__ __forceinline__ void gemm8_rt(const PRef& p, const bf16* __restrict__ A, const bf16* __restrict__ Bt, const int K, const int N, const int epi, const int splitS, float* __restrict__ outp, bf16* shm) {
;     ...
;     if (wr == 0) BAR;
;     const int ntile = tile + gridDim.x;
;     const int cpm = pm, cpn = pn, cks = ks;
;     if (ntile < nwg) { DECODE_TILE(ntile, pm, pn, ks, kofs, nt); PRO_STAGE(pm * BM, pn * BM); }
.LBB0_351:
	s_or_b64 exec, exec, s[0:1]
	s_setprio 0
	v_readlane_b32 s0, v254, 1
	s_add_i32 s72, s72, s0
	s_cmp_ge_i32 s72, s45
	s_cselect_b64 s[22:23], -1, 0
	s_and_b64 vcc, exec, s[22:23]
	s_mov_b32 s75, s25
	s_mov_b32 s73, s24
	s_mov_b32 s74, s26
	v_readlane_b32 s1, v254, 2
	s_cbranch_vccnz .LBB0_358
	s_cmp_ge_i32 s72, s44
	s_mov_b64 s[0:1], -1
	s_cbranch_scc0 .LBB0_354
	s_sub_i32 s0, s72, s44
	s_mul_hi_u32 s1, s0, s67
	s_mul_i32 s4, s1, s40
	s_sub_i32 s4, s0, s4
	s_add_i32 s5, s1, 1
	s_sub_i32 s10, s4, s40
	s_cmp_ge_u32 s4, s40
	s_cselect_b32 s1, s5, s1
	s_cselect_b32 s4, s10, s4
	s_add_i32 s5, s1, 1
	s_cmp_ge_u32 s4, s40
	s_cselect_b32 s74, s5, s1
	s_mul_i32 s1, s74, s40
	s_sub_i32 s73, s0, s1
	s_mul_i32 s0, s74, s68
	s_lshl_b32 s46, s0, 6
	s_mov_b64 s[0:1], 0
